# out-proj (PH7) epilogue output stores write-through (sc1): less dirty L2 data at the phase-end release
# speedup vs baseline: 1.0017x; 1.0002x over previous
; #define SBAR() __builtin_amdgcn_sched_barrier(0)
; __device__ __forceinline__ u32x4 pack8(const f32x4 a, const f32x4 b) { u32x4 w; w.x = cvt_pk_bf16(a[0], a[1]); w.y = cvt_pk_bf16(a[2], a[3]); w.z = cvt_pk_bf16(b[0], b[1]); w.w = cvt_pk_bf16(b[2], b[3]); return w; }
; __device__ __forceinline__ void unpack8(const u32x4 w, f32x4& a, f32x4& b) { a = (f32x4){bf_lo(w.x), bf_hi(w.x), bf_lo(w.y), bf_hi(w.y)}; b = (f32x4){bf_lo(w.z), bf_hi(w.z), bf_lo(w.w), bf_hi(w.w)}; }
;     __device__ __forceinline__ void operator()(f32x4 (&acc)[2][2][4][2], const Unit& u, int wr, int wc, int fr, int fq) const {
;     ...
;         } else if constexpr (PH == 7) {
; #pragma unroll
;             for (int ai = 0; ai < 2; ++ai) { f32x4 xv[4][2][2];
; #pragma unroll
;                 for (int m = 0; m < 4; ++m)
; #pragma unroll
;                     for (int bj = 0; bj < 2; ++bj) { const size_t off = (size_t)ROWOF(ai, m) * DM + u.pn * 256 + bj * 128 + c8; const u32x4 w = *(const u32x4*)(P.xb_() + off); unpack8(w, xv[m][bj][0], xv[m][bj][1]); }
;                 SBAR();
; #pragma unroll
;                 for (int m = 0; m < 4; ++m) { const int row = ROWOF(ai, m); float ss = 0.f;
; #pragma unroll
;                     for (int bj = 0; bj < 2; ++bj) { const size_t off = (size_t)row * DM + u.pn * 256 + bj * 128 + c8;
;                         const f32x4 v0 = acc[ai][bj][m][0] + xv[m][bj][0], v1 = acc[ai][bj][m][1] + xv[m][bj][1]; ss += SSQ8(v0, v1);
;                         *(u32x4*)(P.h1b_() + off) = pack8(v0, v1); }
;                     ss += __shfl_xor(ss, 16); ss += __shfl_xor(ss, 32);
;                     if (fq == 0) atomicAdd(P.ssq_h1_() + row, ss); } }
.LBB0_897:
	v_lshl_add_u32 v172, s30, 8, v189
	s_lshl_b32 s30, s64, 8
	s_ashr_i32 s31, s30, 31
	s_lshl_b64 s[30:31], s[30:31], 1
	v_ashrrev_i32_e32 v173, 31, v172
	v_or_b32_e32 v184, 16, v172
	v_lshl_add_u64 v[174:175], v[166:167], 0, s[30:31]
	v_lshlrev_b64 v[206:207], 12, v[172:173]
	v_ashrrev_i32_e32 v185, 31, v184
	v_or_b32_e32 v180, 32, v172
	v_lshl_add_u64 v[130:131], v[174:175], 0, v[206:207]
	v_lshlrev_b64 v[186:187], 12, v[184:185]
	v_ashrrev_i32_e32 v181, 31, v180
	v_or_b32_e32 v176, 48, v172
	global_load_dwordx4 v[198:201], v[130:131], off
	global_load_dwordx4 v[202:205], v[130:131], off offset:256
	v_lshl_add_u64 v[130:131], v[174:175], 0, v[186:187]
	v_lshlrev_b64 v[182:183], 12, v[180:181]
	v_ashrrev_i32_e32 v177, 31, v176
	global_load_dwordx4 v[150:153], v[130:131], off
	global_load_dwordx4 v[146:149], v[130:131], off offset:256
	v_lshl_add_u64 v[130:131], v[174:175], 0, v[182:183]
	v_lshlrev_b64 v[178:179], 12, v[176:177]
	global_load_dwordx4 v[142:145], v[130:131], off
	global_load_dwordx4 v[138:141], v[130:131], off offset:256
	v_lshl_add_u64 v[130:131], v[174:175], 0, v[178:179]
	global_load_dwordx4 v[134:137], v[130:131], off
	s_nop 0
	global_load_dwordx4 v[130:133], v[130:131], off offset:256
	v_and_b32_e32 v196, 64, v194
	v_xor_b32_e32 v195, 16, v194
	v_add_u32_e32 v196, 64, v196
	v_xor_b32_e32 v197, 32, v194
	v_cmp_lt_i32_e32 vcc, v195, v196
	s_waitcnt vmcnt(0)
	v_lshlrev_b32_e32 v208, 16, v198
	v_cndmask_b32_e32 v195, v194, v195, vcc
	v_cmp_lt_i32_e32 vcc, v197, v196
	v_lshlrev_b32_e32 v196, 2, v195
	v_and_b32_e32 v209, 0xffff0000, v198
	v_cndmask_b32_e32 v197, v194, v197, vcc
	v_lshlrev_b32_e32 v195, 2, v197
	v_lshlrev_b32_e32 v198, 16, v199
	v_and_b32_e32 v199, 0xffff0000, v199
	v_lshlrev_b32_e32 v210, 16, v200
	v_and_b32_e32 v211, 0xffff0000, v200
	v_lshlrev_b32_e32 v200, 16, v201
	v_and_b32_e32 v201, 0xffff0000, v201
	v_lshlrev_b32_e32 v212, 16, v202
	v_and_b32_e32 v213, 0xffff0000, v202
	v_lshlrev_b32_e32 v202, 16, v203
	v_and_b32_e32 v203, 0xffff0000, v203
	v_lshlrev_b32_e32 v214, 16, v204
	v_and_b32_e32 v215, 0xffff0000, v204
	v_lshlrev_b32_e32 v204, 16, v205
	v_and_b32_e32 v205, 0xffff0000, v205
	v_pk_add_f32 v[128:129], v[128:129], v[198:199]
	v_pk_add_f32 v[126:127], v[126:127], v[208:209]
	v_pk_add_f32 v[198:199], v[124:125], v[200:201]
	v_pk_add_f32 v[124:125], v[122:123], v[210:211]
	v_mul_f32_e32 v122, v127, v127
	v_mul_f32_e32 v123, v129, v129
	v_fmac_f32_e32 v122, v126, v126
	v_fmac_f32_e32 v123, v128, v128
	v_add_f32_e32 v122, v122, v123
	v_mul_f32_e32 v123, v125, v125
	v_fmac_f32_e32 v123, v124, v124
	v_add_f32_e32 v122, v123, v122
	v_mul_f32_e32 v123, v199, v199
	v_fmac_f32_e32 v123, v198, v198
	v_add_f32_e32 v197, v123, v122
	v_cvt_pk_bf16_f32 v122, v126, v127
	v_lshl_add_u64 v[126:127], s[14:15], 0, v[206:207]
	v_lshl_add_u64 v[126:127], v[126:127], 0, s[30:31]
	v_cvt_pk_bf16_f32 v123, v128, v129
	v_cvt_pk_bf16_f32 v124, v124, v125
	v_cvt_pk_bf16_f32 v125, v198, v199
	v_lshl_add_u64 v[126:127], v[126:127], 0, v[158:159]
	v_pk_add_f32 v[120:121], v[120:121], v[202:203]
	v_pk_add_f32 v[118:119], v[118:119], v[212:213]
	global_store_dwordx4 v[126:127], v[122:125], off sc1
	v_pk_add_f32 v[114:115], v[114:115], v[214:215]
	s_nop 0
	v_pk_add_f32 v[122:123], v[116:117], v[204:205]
	v_mul_f32_e32 v116, v119, v119
	v_mul_f32_e32 v117, v121, v121
	v_fmac_f32_e32 v116, v118, v118
	v_fmac_f32_e32 v117, v120, v120
	v_add_f32_e32 v116, v116, v117
	v_mul_f32_e32 v117, v115, v115
	v_fmac_f32_e32 v117, v114, v114
	v_add_f32_e32 v116, v117, v116
	v_mul_f32_e32 v117, v123, v123
	v_fmac_f32_e32 v117, v122, v122
	v_add_f32_e32 v116, v117, v116
	v_add_f32_e32 v124, v197, v116
	v_cvt_pk_bf16_f32 v116, v118, v119
	v_cvt_pk_bf16_f32 v119, v122, v123
	ds_bpermute_b32 v122, v196, v124
	v_cvt_pk_bf16_f32 v118, v114, v115
	v_lshl_add_u64 v[114:115], s[86:87], 0, v[206:207]
	v_lshl_add_u64 v[114:115], v[114:115], 0, s[30:31]
	v_cvt_pk_bf16_f32 v117, v120, v121
	v_lshl_add_u64 v[120:121], v[114:115], 0, v[158:159]
	s_waitcnt lgkmcnt(0)
	v_add_f32_e32 v114, v124, v122
	ds_bpermute_b32 v115, v195, v114
	v_add_co_u32_e32 v120, vcc, 0x400000, v120
	s_nop 1
	v_addc_co_u32_e32 v121, vcc, 0, v121, vcc
	global_store_dwordx4 v[120:121], v[116:119], off offset:256 sc1
	s_and_saveexec_b64 s[36:37], s[0:1]
	s_cbranch_execz .LBB0_899
	v_lshl_add_u64 v[116:117], v[172:173], 2, s[16:17]
	s_waitcnt lgkmcnt(0)
	v_add_f32_e32 v114, v114, v115
	global_atomic_add_f32 v[116:117], v114, off
; __device__ __forceinline__ u32x4 pack8(const f32x4 a, const f32x4 b) { u32x4 w; w.x = cvt_pk_bf16(a[0], a[1]); w.y = cvt_pk_bf16(a[2], a[3]); w.z = cvt_pk_bf16(b[0], b[1]); w.w = cvt_pk_bf16(b[2], b[3]); return w; }
;     __device__ __forceinline__ void operator()(f32x4 (&acc)[2][2][4][2], const Unit& u, int wr, int wc, int fr, int fq) const {
;     ...
;                 for (int m = 0; m < 4; ++m) { const int row = ROWOF(ai, m); float ss = 0.f;
; #pragma unroll
;                     for (int bj = 0; bj < 2; ++bj) { const size_t off = (size_t)row * DM + u.pn * 256 + bj * 128 + c8;
;                         const f32x4 v0 = acc[ai][bj][m][0] + xv[m][bj][0], v1 = acc[ai][bj][m][1] + xv[m][bj][1]; ss += SSQ8(v0, v1);
;                         *(u32x4*)(P.h1b_() + off) = pack8(v0, v1); }
;                     ss += __shfl_xor(ss, 16); ss += __shfl_xor(ss, 32);
;                     if (fq == 0) atomicAdd(P.ssq_h1_() + row, ss); } }
.LBB0_899:
	s_or_b64 exec, exec, s[36:37]
	v_lshlrev_b32_e32 v114, 16, v150
	s_waitcnt lgkmcnt(0)
	v_and_b32_e32 v115, 0xffff0000, v150
	v_lshlrev_b32_e32 v116, 16, v151
	v_and_b32_e32 v117, 0xffff0000, v151
	v_lshlrev_b32_e32 v118, 16, v152
	v_and_b32_e32 v119, 0xffff0000, v152
	v_lshlrev_b32_e32 v120, 16, v153
	v_and_b32_e32 v121, 0xffff0000, v153
	v_pk_add_f32 v[112:113], v[112:113], v[116:117]
	v_pk_add_f32 v[110:111], v[110:111], v[114:115]
	v_pk_add_f32 v[114:115], v[108:109], v[120:121]
	v_pk_add_f32 v[108:109], v[106:107], v[118:119]
	v_mul_f32_e32 v106, v111, v111
	v_mul_f32_e32 v107, v113, v113
	v_fmac_f32_e32 v106, v110, v110
	v_fmac_f32_e32 v107, v112, v112
	v_add_f32_e32 v106, v106, v107
	v_mul_f32_e32 v107, v109, v109
	v_fmac_f32_e32 v107, v108, v108
	v_add_f32_e32 v106, v107, v106
	v_mul_f32_e32 v107, v115, v115
	v_fmac_f32_e32 v107, v114, v114
	v_add_f32_e32 v116, v107, v106
	v_cvt_pk_bf16_f32 v106, v110, v111
	v_lshl_add_u64 v[110:111], s[14:15], 0, v[186:187]
	v_lshlrev_b32_e32 v122, 16, v146
	v_and_b32_e32 v123, 0xffff0000, v146
	v_lshlrev_b32_e32 v124, 16, v147
	v_and_b32_e32 v125, 0xffff0000, v147
	v_lshl_add_u64 v[110:111], v[110:111], 0, s[30:31]
	v_lshlrev_b32_e32 v128, 16, v149
	v_and_b32_e32 v129, 0xffff0000, v149
	v_cvt_pk_bf16_f32 v107, v112, v113
	v_cvt_pk_bf16_f32 v108, v108, v109
	v_cvt_pk_bf16_f32 v109, v114, v115
	v_lshl_add_u64 v[110:111], v[110:111], 0, v[158:159]
	v_pk_add_f32 v[104:105], v[104:105], v[124:125]
	v_pk_add_f32 v[102:103], v[102:103], v[122:123]
	v_lshlrev_b32_e32 v126, 16, v148
	v_and_b32_e32 v127, 0xffff0000, v148
	global_store_dwordx4 v[110:111], v[106:109], off sc1
	v_pk_add_f32 v[98:99], v[98:99], v[126:127]
	s_nop 0
	v_pk_add_f32 v[106:107], v[100:101], v[128:129]
	v_mul_f32_e32 v100, v103, v103
	v_mul_f32_e32 v101, v105, v105
	v_fmac_f32_e32 v100, v102, v102
	v_fmac_f32_e32 v101, v104, v104
	v_add_f32_e32 v100, v100, v101
	v_mul_f32_e32 v101, v99, v99
	v_fmac_f32_e32 v101, v98, v98
	v_add_f32_e32 v100, v101, v100
	v_mul_f32_e32 v101, v107, v107
	v_fmac_f32_e32 v101, v106, v106
	v_add_f32_e32 v100, v101, v100
	v_add_f32_e32 v108, v116, v100
	v_cvt_pk_bf16_f32 v100, v102, v103
	v_cvt_pk_bf16_f32 v103, v106, v107
	ds_bpermute_b32 v106, v196, v108
	v_cvt_pk_bf16_f32 v102, v98, v99
	v_lshl_add_u64 v[98:99], s[86:87], 0, v[186:187]
	v_lshl_add_u64 v[98:99], v[98:99], 0, s[30:31]
	v_cvt_pk_bf16_f32 v101, v104, v105
	v_lshl_add_u64 v[104:105], v[98:99], 0, v[158:159]
	s_waitcnt lgkmcnt(0)
	v_add_f32_e32 v98, v108, v106
	ds_bpermute_b32 v99, v195, v98
	v_add_co_u32_e32 v104, vcc, 0x400000, v104
	s_nop 1
	v_addc_co_u32_e32 v105, vcc, 0, v105, vcc
	global_store_dwordx4 v[104:105], v[100:103], off offset:256 sc1
	s_and_saveexec_b64 s[36:37], s[0:1]
	s_cbranch_execz .LBB0_901
	v_lshl_add_u64 v[100:101], v[184:185], 2, s[16:17]
	s_waitcnt lgkmcnt(0)
	v_add_f32_e32 v98, v98, v99
	global_atomic_add_f32 v[100:101], v98, off
.LBB0_901:
	s_or_b64 exec, exec, s[36:37]
	v_lshlrev_b32_e32 v98, 16, v142
	s_waitcnt lgkmcnt(0)
	v_and_b32_e32 v99, 0xffff0000, v142
	v_lshlrev_b32_e32 v100, 16, v143
	v_and_b32_e32 v101, 0xffff0000, v143
	v_lshlrev_b32_e32 v102, 16, v144
	v_and_b32_e32 v103, 0xffff0000, v144
	v_lshlrev_b32_e32 v104, 16, v145
	v_and_b32_e32 v105, 0xffff0000, v145
	v_pk_add_f32 v[96:97], v[96:97], v[100:101]
	v_pk_add_f32 v[94:95], v[94:95], v[98:99]
	v_pk_add_f32 v[98:99], v[92:93], v[104:105]
	v_pk_add_f32 v[92:93], v[90:91], v[102:103]
	v_mul_f32_e32 v90, v95, v95
	v_mul_f32_e32 v91, v97, v97
	v_fmac_f32_e32 v90, v94, v94
	v_fmac_f32_e32 v91, v96, v96
	v_add_f32_e32 v90, v90, v91
	v_mul_f32_e32 v91, v93, v93
	v_fmac_f32_e32 v91, v92, v92
	v_add_f32_e32 v90, v91, v90
	v_mul_f32_e32 v91, v99, v99
	v_fmac_f32_e32 v91, v98, v98
	v_add_f32_e32 v100, v91, v90
	v_cvt_pk_bf16_f32 v90, v94, v95
	v_lshl_add_u64 v[94:95], s[14:15], 0, v[182:183]
	v_lshlrev_b32_e32 v106, 16, v138
	v_and_b32_e32 v107, 0xffff0000, v138
	v_lshlrev_b32_e32 v108, 16, v139
	v_and_b32_e32 v109, 0xffff0000, v139
	v_lshl_add_u64 v[94:95], v[94:95], 0, s[30:31]
	v_lshlrev_b32_e32 v112, 16, v141
	v_and_b32_e32 v113, 0xffff0000, v141
	v_cvt_pk_bf16_f32 v91, v96, v97
	v_cvt_pk_bf16_f32 v92, v92, v93
	v_cvt_pk_bf16_f32 v93, v98, v99
	v_lshl_add_u64 v[94:95], v[94:95], 0, v[158:159]
	v_pk_add_f32 v[88:89], v[88:89], v[108:109]
	v_pk_add_f32 v[86:87], v[86:87], v[106:107]
	v_lshlrev_b32_e32 v110, 16, v140
	v_and_b32_e32 v111, 0xffff0000, v140
	global_store_dwordx4 v[94:95], v[90:93], off sc1
	v_pk_add_f32 v[82:83], v[82:83], v[110:111]
	s_nop 0
	v_pk_add_f32 v[90:91], v[84:85], v[112:113]
	v_mul_f32_e32 v84, v87, v87
	v_mul_f32_e32 v85, v89, v89
	v_fmac_f32_e32 v84, v86, v86
	v_fmac_f32_e32 v85, v88, v88
	v_add_f32_e32 v84, v84, v85
	v_mul_f32_e32 v85, v83, v83
	v_fmac_f32_e32 v85, v82, v82
	v_add_f32_e32 v84, v85, v84
	v_mul_f32_e32 v85, v91, v91
	v_fmac_f32_e32 v85, v90, v90
	v_add_f32_e32 v84, v85, v84
	v_add_f32_e32 v92, v100, v84
	v_cvt_pk_bf16_f32 v84, v86, v87
	v_cvt_pk_bf16_f32 v87, v90, v91
	ds_bpermute_b32 v90, v196, v92
	v_cvt_pk_bf16_f32 v86, v82, v83
	v_lshl_add_u64 v[82:83], s[86:87], 0, v[182:183]
	v_lshl_add_u64 v[82:83], v[82:83], 0, s[30:31]
	v_cvt_pk_bf16_f32 v85, v88, v89
	v_lshl_add_u64 v[88:89], v[82:83], 0, v[158:159]
	s_waitcnt lgkmcnt(0)
	v_add_f32_e32 v82, v92, v90
	ds_bpermute_b32 v83, v195, v82
	v_add_co_u32_e32 v88, vcc, 0x400000, v88
	s_nop 1
	v_addc_co_u32_e32 v89, vcc, 0, v89, vcc
	global_store_dwordx4 v[88:89], v[84:87], off offset:256 sc1
	s_and_saveexec_b64 s[36:37], s[0:1]
	s_cbranch_execz .LBB0_903
	v_lshl_add_u64 v[84:85], v[180:181], 2, s[16:17]
	s_waitcnt lgkmcnt(0)
	v_add_f32_e32 v82, v82, v83
	global_atomic_add_f32 v[84:85], v82, off
; #define SBAR() __builtin_amdgcn_sched_barrier(0)
; __device__ __forceinline__ u32x4 pack8(const f32x4 a, const f32x4 b) { u32x4 w; w.x = cvt_pk_bf16(a[0], a[1]); w.y = cvt_pk_bf16(a[2], a[3]); w.z = cvt_pk_bf16(b[0], b[1]); w.w = cvt_pk_bf16(b[2], b[3]); return w; }
; __device__ __forceinline__ void unpack8(const u32x4 w, f32x4& a, f32x4& b) { a = (f32x4){bf_lo(w.x), bf_hi(w.x), bf_lo(w.y), bf_hi(w.y)}; b = (f32x4){bf_lo(w.z), bf_hi(w.z), bf_lo(w.w), bf_hi(w.w)}; }
;     __device__ __forceinline__ void operator()(f32x4 (&acc)[2][2][4][2], const Unit& u, int wr, int wc, int fr, int fq) const {
;     ...
;             for (int ai = 0; ai < 2; ++ai) { f32x4 xv[4][2][2];
; #pragma unroll
;                 for (int m = 0; m < 4; ++m)
; #pragma unroll
;                     for (int bj = 0; bj < 2; ++bj) { const size_t off = (size_t)ROWOF(ai, m) * DM + u.pn * 256 + bj * 128 + c8; const u32x4 w = *(const u32x4*)(P.xb_() + off); unpack8(w, xv[m][bj][0], xv[m][bj][1]); }
;                 SBAR();
; #pragma unroll
;                 for (int m = 0; m < 4; ++m) { const int row = ROWOF(ai, m); float ss = 0.f;
; #pragma unroll
;                     for (int bj = 0; bj < 2; ++bj) { const size_t off = (size_t)row * DM + u.pn * 256 + bj * 128 + c8;
;                         const f32x4 v0 = acc[ai][bj][m][0] + xv[m][bj][0], v1 = acc[ai][bj][m][1] + xv[m][bj][1]; ss += SSQ8(v0, v1);
;                         *(u32x4*)(P.h1b_() + off) = pack8(v0, v1); }
;                     ss += __shfl_xor(ss, 16); ss += __shfl_xor(ss, 32);
;                     if (fq == 0) atomicAdd(P.ssq_h1_() + row, ss); } }
.LBB0_903:
	s_or_b64 exec, exec, s[36:37]
	v_lshlrev_b32_e32 v82, 16, v134
	s_waitcnt lgkmcnt(0)
	v_and_b32_e32 v83, 0xffff0000, v134
	v_lshlrev_b32_e32 v84, 16, v135
	v_and_b32_e32 v85, 0xffff0000, v135
	v_lshlrev_b32_e32 v86, 16, v136
	v_and_b32_e32 v87, 0xffff0000, v136
	v_lshlrev_b32_e32 v88, 16, v137
	v_and_b32_e32 v89, 0xffff0000, v137
	v_pk_add_f32 v[80:81], v[80:81], v[84:85]
	v_pk_add_f32 v[78:79], v[78:79], v[82:83]
	v_pk_add_f32 v[82:83], v[76:77], v[88:89]
	v_pk_add_f32 v[76:77], v[74:75], v[86:87]
	v_mul_f32_e32 v74, v79, v79
	v_mul_f32_e32 v75, v81, v81
	v_fmac_f32_e32 v74, v78, v78
	v_fmac_f32_e32 v75, v80, v80
	v_add_f32_e32 v74, v74, v75
	v_mul_f32_e32 v75, v77, v77
	v_fmac_f32_e32 v75, v76, v76
	v_add_f32_e32 v74, v75, v74
	v_mul_f32_e32 v75, v83, v83
	v_fmac_f32_e32 v75, v82, v82
	v_add_f32_e32 v84, v75, v74
	v_cvt_pk_bf16_f32 v74, v78, v79
	v_lshl_add_u64 v[78:79], s[14:15], 0, v[178:179]
	v_lshlrev_b32_e32 v90, 16, v130
	v_and_b32_e32 v91, 0xffff0000, v130
	v_lshlrev_b32_e32 v92, 16, v131
	v_and_b32_e32 v93, 0xffff0000, v131
	v_lshl_add_u64 v[78:79], v[78:79], 0, s[30:31]
	v_lshlrev_b32_e32 v96, 16, v133
	v_and_b32_e32 v97, 0xffff0000, v133
	v_cvt_pk_bf16_f32 v75, v80, v81
	v_cvt_pk_bf16_f32 v76, v76, v77
	v_cvt_pk_bf16_f32 v77, v82, v83
	v_lshl_add_u64 v[78:79], v[78:79], 0, v[158:159]
	v_pk_add_f32 v[72:73], v[72:73], v[92:93]
	v_pk_add_f32 v[70:71], v[70:71], v[90:91]
	v_lshlrev_b32_e32 v94, 16, v132
	v_and_b32_e32 v95, 0xffff0000, v132
	global_store_dwordx4 v[78:79], v[74:77], off sc1
	v_pk_add_f32 v[66:67], v[66:67], v[94:95]
	s_nop 0
	v_pk_add_f32 v[74:75], v[68:69], v[96:97]
	v_mul_f32_e32 v68, v71, v71
	v_mul_f32_e32 v69, v73, v73
	v_fmac_f32_e32 v68, v70, v70
	v_fmac_f32_e32 v69, v72, v72
	v_add_f32_e32 v68, v68, v69
	v_mul_f32_e32 v69, v67, v67
	v_fmac_f32_e32 v69, v66, v66
	v_add_f32_e32 v68, v69, v68
	v_mul_f32_e32 v69, v75, v75
	v_fmac_f32_e32 v69, v74, v74
	v_add_f32_e32 v68, v69, v68
	v_add_f32_e32 v76, v84, v68
	v_cvt_pk_bf16_f32 v68, v70, v71
	v_cvt_pk_bf16_f32 v71, v74, v75
	ds_bpermute_b32 v74, v196, v76
	v_cvt_pk_bf16_f32 v70, v66, v67
	v_lshl_add_u64 v[66:67], s[86:87], 0, v[178:179]
	v_lshl_add_u64 v[66:67], v[66:67], 0, s[30:31]
	v_cvt_pk_bf16_f32 v69, v72, v73
	v_lshl_add_u64 v[72:73], v[66:67], 0, v[158:159]
	s_waitcnt lgkmcnt(0)
	v_add_f32_e32 v66, v76, v74
	ds_bpermute_b32 v67, v195, v66
	v_add_co_u32_e32 v72, vcc, 0x400000, v72
	s_nop 1
	v_addc_co_u32_e32 v73, vcc, 0, v73, vcc
	global_store_dwordx4 v[72:73], v[68:71], off offset:256 sc1
	s_and_saveexec_b64 s[36:37], s[0:1]
	s_cbranch_execz .LBB0_905
	v_lshl_add_u64 v[68:69], v[176:177], 2, s[16:17]
	s_waitcnt lgkmcnt(0)
	v_add_f32_e32 v66, v66, v67
	global_atomic_add_f32 v[68:69], v66, off
.LBB0_905:
	s_or_b64 exec, exec, s[36:37]
	v_add_u32_e32 v102, 0x80, v172
	v_ashrrev_i32_e32 v103, 31, v102
	v_add_u32_e32 v98, 0x90, v172
	v_lshlrev_b64 v[112:113], 12, v[102:103]
	v_ashrrev_i32_e32 v99, 31, v98
	v_add_u32_e32 v94, 0xa0, v172
	s_waitcnt lgkmcnt(0)
	v_lshl_add_u64 v[66:67], v[174:175], 0, v[112:113]
	v_lshlrev_b64 v[100:101], 12, v[98:99]
	v_ashrrev_i32_e32 v95, 31, v94
	v_add_u32_e32 v90, 0xb0, v172
	global_load_dwordx4 v[104:107], v[66:67], off
	global_load_dwordx4 v[108:111], v[66:67], off offset:256
	v_lshl_add_u64 v[66:67], v[174:175], 0, v[100:101]
	v_lshlrev_b64 v[96:97], 12, v[94:95]
	v_ashrrev_i32_e32 v91, 31, v90
	global_load_dwordx4 v[86:89], v[66:67], off
	global_load_dwordx4 v[82:85], v[66:67], off offset:256
	v_lshl_add_u64 v[66:67], v[174:175], 0, v[96:97]
	v_lshlrev_b64 v[92:93], 12, v[90:91]
	global_load_dwordx4 v[78:81], v[66:67], off
	global_load_dwordx4 v[74:77], v[66:67], off offset:256
	v_lshl_add_u64 v[66:67], v[174:175], 0, v[92:93]
	global_load_dwordx4 v[70:73], v[66:67], off
	s_nop 0
	global_load_dwordx4 v[66:69], v[66:67], off offset:256
	s_waitcnt vmcnt(7)
	v_lshlrev_b32_e32 v114, 16, v104
	v_and_b32_e32 v115, 0xffff0000, v104
	v_lshlrev_b32_e32 v104, 16, v105
	v_and_b32_e32 v105, 0xffff0000, v105
	v_lshlrev_b32_e32 v116, 16, v106
	v_and_b32_e32 v117, 0xffff0000, v106
	v_lshlrev_b32_e32 v106, 16, v107
	v_and_b32_e32 v107, 0xffff0000, v107
	s_waitcnt vmcnt(6)
	v_lshlrev_b32_e32 v118, 16, v108
	v_and_b32_e32 v119, 0xffff0000, v108
	v_lshlrev_b32_e32 v108, 16, v109
	v_and_b32_e32 v109, 0xffff0000, v109
	v_lshlrev_b32_e32 v120, 16, v110
	v_and_b32_e32 v121, 0xffff0000, v110
	v_lshlrev_b32_e32 v110, 16, v111
	v_and_b32_e32 v111, 0xffff0000, v111
	v_pk_add_f32 v[64:65], v[64:65], v[104:105]
	v_pk_add_f32 v[62:63], v[62:63], v[114:115]
	v_pk_add_f32 v[104:105], v[60:61], v[106:107]
	v_pk_add_f32 v[60:61], v[58:59], v[116:117]
	v_mul_f32_e32 v58, v63, v63
	v_mul_f32_e32 v59, v65, v65
	v_fmac_f32_e32 v58, v62, v62
	v_fmac_f32_e32 v59, v64, v64
	v_add_f32_e32 v58, v58, v59
	v_mul_f32_e32 v59, v61, v61
	v_fmac_f32_e32 v59, v60, v60
	v_add_f32_e32 v58, v59, v58
	v_mul_f32_e32 v59, v105, v105
	v_fmac_f32_e32 v59, v104, v104
	v_add_f32_e32 v106, v59, v58
	v_cvt_pk_bf16_f32 v58, v62, v63
	v_lshl_add_u64 v[62:63], s[14:15], 0, v[112:113]
	v_lshl_add_u64 v[62:63], v[62:63], 0, s[30:31]
	v_cvt_pk_bf16_f32 v59, v64, v65
	v_cvt_pk_bf16_f32 v60, v60, v61
	v_cvt_pk_bf16_f32 v61, v104, v105
	v_lshl_add_u64 v[62:63], v[62:63], 0, v[158:159]
	v_pk_add_f32 v[56:57], v[56:57], v[108:109]
	v_pk_add_f32 v[54:55], v[54:55], v[118:119]
	global_store_dwordx4 v[62:63], v[58:61], off sc1
	v_pk_add_f32 v[50:51], v[50:51], v[120:121]
	s_nop 0
	v_pk_add_f32 v[58:59], v[52:53], v[110:111]
	v_mul_f32_e32 v52, v55, v55
	v_mul_f32_e32 v53, v57, v57
	v_fmac_f32_e32 v52, v54, v54
	v_fmac_f32_e32 v53, v56, v56
	v_add_f32_e32 v52, v52, v53
	v_mul_f32_e32 v53, v51, v51
	v_fmac_f32_e32 v53, v50, v50
	v_add_f32_e32 v52, v53, v52
	v_mul_f32_e32 v53, v59, v59
	v_fmac_f32_e32 v53, v58, v58
	v_add_f32_e32 v52, v53, v52
	v_add_f32_e32 v60, v106, v52
	v_cvt_pk_bf16_f32 v52, v54, v55
	v_cvt_pk_bf16_f32 v55, v58, v59
	ds_bpermute_b32 v58, v196, v60
	v_cvt_pk_bf16_f32 v54, v50, v51
	v_lshl_add_u64 v[50:51], s[86:87], 0, v[112:113]
	v_lshl_add_u64 v[50:51], v[50:51], 0, s[30:31]
	v_cvt_pk_bf16_f32 v53, v56, v57
	v_lshl_add_u64 v[56:57], v[50:51], 0, v[158:159]
	s_waitcnt lgkmcnt(0)
	v_add_f32_e32 v50, v60, v58
	ds_bpermute_b32 v51, v195, v50
	v_add_co_u32_e32 v56, vcc, 0x400000, v56
	s_nop 1
	v_addc_co_u32_e32 v57, vcc, 0, v57, vcc
	global_store_dwordx4 v[56:57], v[52:55], off offset:256 sc1
	s_and_saveexec_b64 s[36:37], s[0:1]
	s_cbranch_execz .LBB0_907
	v_lshl_add_u64 v[52:53], v[102:103], 2, s[16:17]
	s_waitcnt lgkmcnt(0)
	v_add_f32_e32 v50, v50, v51
	global_atomic_add_f32 v[52:53], v50, off
; __device__ __forceinline__ u32x4 pack8(const f32x4 a, const f32x4 b) { u32x4 w; w.x = cvt_pk_bf16(a[0], a[1]); w.y = cvt_pk_bf16(a[2], a[3]); w.z = cvt_pk_bf16(b[0], b[1]); w.w = cvt_pk_bf16(b[2], b[3]); return w; }
;     __device__ __forceinline__ void operator()(f32x4 (&acc)[2][2][4][2], const Unit& u, int wr, int wc, int fr, int fq) const {
;     ...
;                 for (int m = 0; m < 4; ++m) { const int row = ROWOF(ai, m); float ss = 0.f;
; #pragma unroll
;                     for (int bj = 0; bj < 2; ++bj) { const size_t off = (size_t)row * DM + u.pn * 256 + bj * 128 + c8;
;                         const f32x4 v0 = acc[ai][bj][m][0] + xv[m][bj][0], v1 = acc[ai][bj][m][1] + xv[m][bj][1]; ss += SSQ8(v0, v1);
;                         *(u32x4*)(P.h1b_() + off) = pack8(v0, v1); }
;                     ss += __shfl_xor(ss, 16); ss += __shfl_xor(ss, 32);
;                     if (fq == 0) atomicAdd(P.ssq_h1_() + row, ss); } }
.LBB0_907:
	s_or_b64 exec, exec, s[36:37]
	s_waitcnt vmcnt(7)
	v_lshlrev_b32_e32 v50, 16, v86
	s_waitcnt lgkmcnt(0)
	v_and_b32_e32 v51, 0xffff0000, v86
	v_lshlrev_b32_e32 v52, 16, v87
	v_and_b32_e32 v53, 0xffff0000, v87
	v_lshlrev_b32_e32 v54, 16, v88
	v_and_b32_e32 v55, 0xffff0000, v88
	v_lshlrev_b32_e32 v56, 16, v89
	v_and_b32_e32 v57, 0xffff0000, v89
	v_pk_add_f32 v[48:49], v[48:49], v[52:53]
	v_pk_add_f32 v[46:47], v[46:47], v[50:51]
	v_pk_add_f32 v[50:51], v[44:45], v[56:57]
	v_pk_add_f32 v[44:45], v[42:43], v[54:55]
	v_mul_f32_e32 v42, v47, v47
	v_mul_f32_e32 v43, v49, v49
	v_fmac_f32_e32 v42, v46, v46
	v_fmac_f32_e32 v43, v48, v48
	v_add_f32_e32 v42, v42, v43
	v_mul_f32_e32 v43, v45, v45
	v_fmac_f32_e32 v43, v44, v44
	v_add_f32_e32 v42, v43, v42
	v_mul_f32_e32 v43, v51, v51
	v_fmac_f32_e32 v43, v50, v50
	v_add_f32_e32 v52, v43, v42
	v_cvt_pk_bf16_f32 v42, v46, v47
	v_lshl_add_u64 v[46:47], s[14:15], 0, v[100:101]
	s_waitcnt vmcnt(6)
	v_lshlrev_b32_e32 v58, 16, v82
	v_and_b32_e32 v59, 0xffff0000, v82
	v_lshlrev_b32_e32 v60, 16, v83
	v_and_b32_e32 v61, 0xffff0000, v83
	v_lshl_add_u64 v[46:47], v[46:47], 0, s[30:31]
	v_lshlrev_b32_e32 v64, 16, v85
	v_and_b32_e32 v65, 0xffff0000, v85
	v_cvt_pk_bf16_f32 v43, v48, v49
	v_cvt_pk_bf16_f32 v44, v44, v45
	v_cvt_pk_bf16_f32 v45, v50, v51
	v_lshl_add_u64 v[46:47], v[46:47], 0, v[158:159]
	v_pk_add_f32 v[40:41], v[40:41], v[60:61]
	v_pk_add_f32 v[38:39], v[38:39], v[58:59]
	v_lshlrev_b32_e32 v62, 16, v84
	v_and_b32_e32 v63, 0xffff0000, v84
	global_store_dwordx4 v[46:47], v[42:45], off sc1
	v_pk_add_f32 v[34:35], v[34:35], v[62:63]
	s_nop 0
	v_pk_add_f32 v[42:43], v[36:37], v[64:65]
	v_mul_f32_e32 v36, v39, v39
	v_mul_f32_e32 v37, v41, v41
	v_fmac_f32_e32 v36, v38, v38
	v_fmac_f32_e32 v37, v40, v40
	v_add_f32_e32 v36, v36, v37
	v_mul_f32_e32 v37, v35, v35
	v_fmac_f32_e32 v37, v34, v34
	v_add_f32_e32 v36, v37, v36
	v_mul_f32_e32 v37, v43, v43
	v_fmac_f32_e32 v37, v42, v42
	v_add_f32_e32 v36, v37, v36
	v_add_f32_e32 v44, v52, v36
	v_cvt_pk_bf16_f32 v36, v38, v39
	v_cvt_pk_bf16_f32 v39, v42, v43
	ds_bpermute_b32 v42, v196, v44
	v_cvt_pk_bf16_f32 v38, v34, v35
	v_lshl_add_u64 v[34:35], s[86:87], 0, v[100:101]
	v_lshl_add_u64 v[34:35], v[34:35], 0, s[30:31]
	v_cvt_pk_bf16_f32 v37, v40, v41
	v_lshl_add_u64 v[40:41], v[34:35], 0, v[158:159]
	s_waitcnt lgkmcnt(0)
	v_add_f32_e32 v34, v44, v42
	ds_bpermute_b32 v35, v195, v34
	v_add_co_u32_e32 v40, vcc, 0x400000, v40
	s_nop 1
	v_addc_co_u32_e32 v41, vcc, 0, v41, vcc
	global_store_dwordx4 v[40:41], v[36:39], off offset:256 sc1
	s_and_saveexec_b64 s[36:37], s[0:1]
	s_cbranch_execz .LBB0_909
	v_lshl_add_u64 v[36:37], v[98:99], 2, s[16:17]
	s_waitcnt lgkmcnt(0)
	v_add_f32_e32 v34, v34, v35
	global_atomic_add_f32 v[36:37], v34, off
; __device__ __forceinline__ u32x4 pack8(const f32x4 a, const f32x4 b) { u32x4 w; w.x = cvt_pk_bf16(a[0], a[1]); w.y = cvt_pk_bf16(a[2], a[3]); w.z = cvt_pk_bf16(b[0], b[1]); w.w = cvt_pk_bf16(b[2], b[3]); return w; }
;     __device__ __forceinline__ void operator()(f32x4 (&acc)[2][2][4][2], const Unit& u, int wr, int wc, int fr, int fq) const {
;     ...
;                 for (int m = 0; m < 4; ++m) { const int row = ROWOF(ai, m); float ss = 0.f;
; #pragma unroll
;                     for (int bj = 0; bj < 2; ++bj) { const size_t off = (size_t)row * DM + u.pn * 256 + bj * 128 + c8;
;                         const f32x4 v0 = acc[ai][bj][m][0] + xv[m][bj][0], v1 = acc[ai][bj][m][1] + xv[m][bj][1]; ss += SSQ8(v0, v1);
;                         *(u32x4*)(P.h1b_() + off) = pack8(v0, v1); }
;                     ss += __shfl_xor(ss, 16); ss += __shfl_xor(ss, 32);
;                     if (fq == 0) atomicAdd(P.ssq_h1_() + row, ss); } }
.LBB0_909:
	s_or_b64 exec, exec, s[36:37]
	s_waitcnt vmcnt(7)
	v_lshlrev_b32_e32 v34, 16, v78
	s_waitcnt lgkmcnt(0)
	v_and_b32_e32 v35, 0xffff0000, v78
	v_lshlrev_b32_e32 v36, 16, v79
	v_and_b32_e32 v37, 0xffff0000, v79
	v_lshlrev_b32_e32 v38, 16, v80
	v_and_b32_e32 v39, 0xffff0000, v80
	v_lshlrev_b32_e32 v40, 16, v81
	v_and_b32_e32 v41, 0xffff0000, v81
	v_pk_add_f32 v[32:33], v[32:33], v[36:37]
	v_pk_add_f32 v[30:31], v[30:31], v[34:35]
	v_pk_add_f32 v[34:35], v[28:29], v[40:41]
	v_pk_add_f32 v[28:29], v[26:27], v[38:39]
	v_mul_f32_e32 v26, v31, v31
	v_mul_f32_e32 v27, v33, v33
	v_fmac_f32_e32 v26, v30, v30
	v_fmac_f32_e32 v27, v32, v32
	v_add_f32_e32 v26, v26, v27
	v_mul_f32_e32 v27, v29, v29
	v_fmac_f32_e32 v27, v28, v28
	v_add_f32_e32 v26, v27, v26
	v_mul_f32_e32 v27, v35, v35
	v_fmac_f32_e32 v27, v34, v34
	v_add_f32_e32 v36, v27, v26
	v_cvt_pk_bf16_f32 v26, v30, v31
	v_lshl_add_u64 v[30:31], s[14:15], 0, v[96:97]
	s_waitcnt vmcnt(6)
	v_lshlrev_b32_e32 v42, 16, v74
	v_and_b32_e32 v43, 0xffff0000, v74
	v_lshlrev_b32_e32 v44, 16, v75
	v_and_b32_e32 v45, 0xffff0000, v75
	v_lshl_add_u64 v[30:31], v[30:31], 0, s[30:31]
	v_lshlrev_b32_e32 v48, 16, v77
	v_and_b32_e32 v49, 0xffff0000, v77
	v_cvt_pk_bf16_f32 v27, v32, v33
	v_cvt_pk_bf16_f32 v28, v28, v29
	v_cvt_pk_bf16_f32 v29, v34, v35
	v_lshl_add_u64 v[30:31], v[30:31], 0, v[158:159]
	v_pk_add_f32 v[24:25], v[24:25], v[44:45]
	v_pk_add_f32 v[22:23], v[22:23], v[42:43]
	v_lshlrev_b32_e32 v46, 16, v76
	v_and_b32_e32 v47, 0xffff0000, v76
	global_store_dwordx4 v[30:31], v[26:29], off sc1
	v_pk_add_f32 v[18:19], v[18:19], v[46:47]
	s_nop 0
	v_pk_add_f32 v[26:27], v[20:21], v[48:49]
	v_mul_f32_e32 v20, v23, v23
	v_mul_f32_e32 v21, v25, v25
	v_fmac_f32_e32 v20, v22, v22
	v_fmac_f32_e32 v21, v24, v24
	v_add_f32_e32 v20, v20, v21
	v_mul_f32_e32 v21, v19, v19
	v_fmac_f32_e32 v21, v18, v18
	v_add_f32_e32 v20, v21, v20
	v_mul_f32_e32 v21, v27, v27
	v_fmac_f32_e32 v21, v26, v26
	v_add_f32_e32 v20, v21, v20
	v_add_f32_e32 v28, v36, v20
	v_cvt_pk_bf16_f32 v20, v22, v23
	v_cvt_pk_bf16_f32 v23, v26, v27
	ds_bpermute_b32 v26, v196, v28
	v_cvt_pk_bf16_f32 v22, v18, v19
	v_lshl_add_u64 v[18:19], s[86:87], 0, v[96:97]
	v_lshl_add_u64 v[18:19], v[18:19], 0, s[30:31]
	v_cvt_pk_bf16_f32 v21, v24, v25
	v_lshl_add_u64 v[24:25], v[18:19], 0, v[158:159]
	s_waitcnt lgkmcnt(0)
	v_add_f32_e32 v18, v28, v26
	ds_bpermute_b32 v19, v195, v18
	v_add_co_u32_e32 v24, vcc, 0x400000, v24
	s_nop 1
	v_addc_co_u32_e32 v25, vcc, 0, v25, vcc
	global_store_dwordx4 v[24:25], v[20:23], off offset:256 sc1
	s_and_saveexec_b64 s[36:37], s[0:1]
	s_cbranch_execz .LBB0_911
	v_lshl_add_u64 v[20:21], v[94:95], 2, s[16:17]
	s_waitcnt lgkmcnt(0)
	v_add_f32_e32 v18, v18, v19
	global_atomic_add_f32 v[20:21], v18, off
.LBB0_911:
	s_or_b64 exec, exec, s[36:37]
	s_waitcnt vmcnt(7)
	v_lshlrev_b32_e32 v18, 16, v70
	s_waitcnt lgkmcnt(0)
	v_and_b32_e32 v19, 0xffff0000, v70
	v_lshlrev_b32_e32 v20, 16, v71
	v_and_b32_e32 v21, 0xffff0000, v71
	v_lshlrev_b32_e32 v22, 16, v72
	v_and_b32_e32 v23, 0xffff0000, v72
	v_lshlrev_b32_e32 v24, 16, v73
	v_and_b32_e32 v25, 0xffff0000, v73
	v_pk_add_f32 v[16:17], v[16:17], v[20:21]
	v_pk_add_f32 v[14:15], v[14:15], v[18:19]
	v_pk_add_f32 v[18:19], v[12:13], v[24:25]
	v_pk_add_f32 v[12:13], v[10:11], v[22:23]
	v_mul_f32_e32 v10, v15, v15
	v_mul_f32_e32 v11, v17, v17
	v_fmac_f32_e32 v10, v14, v14
	v_fmac_f32_e32 v11, v16, v16
	v_add_f32_e32 v10, v10, v11
	v_mul_f32_e32 v11, v13, v13
	v_fmac_f32_e32 v11, v12, v12
	v_add_f32_e32 v10, v11, v10
	v_mul_f32_e32 v11, v19, v19
	v_fmac_f32_e32 v11, v18, v18
	v_add_f32_e32 v20, v11, v10
	v_cvt_pk_bf16_f32 v10, v14, v15
	v_lshl_add_u64 v[14:15], s[14:15], 0, v[92:93]
	s_waitcnt vmcnt(6)
	v_lshlrev_b32_e32 v26, 16, v66
	v_and_b32_e32 v27, 0xffff0000, v66
	v_lshlrev_b32_e32 v28, 16, v67
	v_and_b32_e32 v29, 0xffff0000, v67
	v_lshl_add_u64 v[14:15], v[14:15], 0, s[30:31]
	v_lshlrev_b32_e32 v32, 16, v69
	v_and_b32_e32 v33, 0xffff0000, v69
	v_cvt_pk_bf16_f32 v11, v16, v17
	v_cvt_pk_bf16_f32 v12, v12, v13
	v_cvt_pk_bf16_f32 v13, v18, v19
	v_lshl_add_u64 v[14:15], v[14:15], 0, v[158:159]
	v_pk_add_f32 v[8:9], v[8:9], v[28:29]
	v_pk_add_f32 v[6:7], v[6:7], v[26:27]
	v_lshlrev_b32_e32 v30, 16, v68
	v_and_b32_e32 v31, 0xffff0000, v68
	global_store_dwordx4 v[14:15], v[10:13], off sc1
	v_pk_add_f32 v[2:3], v[2:3], v[30:31]
	s_nop 0
	v_pk_add_f32 v[10:11], v[4:5], v[32:33]
	v_mul_f32_e32 v4, v7, v7
	v_mul_f32_e32 v5, v9, v9
	v_fmac_f32_e32 v4, v6, v6
	v_fmac_f32_e32 v5, v8, v8
	v_add_f32_e32 v4, v4, v5
	v_mul_f32_e32 v5, v3, v3
	v_fmac_f32_e32 v5, v2, v2
	v_add_f32_e32 v4, v5, v4
	v_mul_f32_e32 v5, v11, v11
	v_fmac_f32_e32 v5, v10, v10
	v_add_f32_e32 v4, v5, v4
	v_add_f32_e32 v12, v20, v4
	v_cvt_pk_bf16_f32 v4, v6, v7
	v_cvt_pk_bf16_f32 v7, v10, v11
	ds_bpermute_b32 v10, v196, v12
	v_cvt_pk_bf16_f32 v6, v2, v3
	v_lshl_add_u64 v[2:3], s[86:87], 0, v[92:93]
	v_lshl_add_u64 v[2:3], v[2:3], 0, s[30:31]
	v_cvt_pk_bf16_f32 v5, v8, v9
	v_lshl_add_u64 v[8:9], v[2:3], 0, v[158:159]
	s_waitcnt lgkmcnt(0)
	v_add_f32_e32 v2, v12, v10
	ds_bpermute_b32 v3, v195, v2
	v_add_co_u32_e32 v8, vcc, 0x400000, v8
	s_nop 1
	v_addc_co_u32_e32 v9, vcc, 0, v9, vcc
	global_store_dwordx4 v[8:9], v[4:7], off offset:256 sc1
	s_and_saveexec_b64 s[30:31], s[0:1]
	s_cbranch_execz .LBB0_913
	v_lshl_add_u64 v[4:5], v[90:91], 2, s[16:17]
	s_waitcnt lgkmcnt(0)
	v_add_f32_e32 v2, v2, v3
	global_atomic_add_f32 v[4:5], v2, off
